# queue pull: claimed index handed to the other waves via ds_write/ds_read instead of flat sc0 sc1 store+load with vmcnt(0)
# speedup vs baseline: 1.0021x; 1.0021x over previous
; DI int tid_opaque() { int t = threadIdx.x; asm volatile("" : "+v"(t)); return t; }
; DI float fexp2(float x) { return __builtin_amdgcn_exp2f(x); }
; __device__ void dilc_item(const Params& p, int item) {
;   const int tid = tid_opaque();
;   const int tokg = item * 64 + (tid >> 3), hh = (tid >> 2) & 1, d0 = (tid & 3) * 16;
;   const int b = tokg >> 13, t = tokg & (SEQ - 1);
;   const float* dilo = (const float*)(p.ws + OFF_DILO);
;   const float* dill = (const float*)(p.ws + OFF_DILL);
;   float ls[3]; const float* op[3];
; #pragma unroll
;   for (int g = 0; g < 3; ++g) {
;     int sh = 2 * g;
;     size_t prow = (size_t)(b * 3 + g) * SEQ + (size_t)(t & ((1 << sh) - 1)) * (SEQ >> sh) + (t >> sh);
;     ls[g] = dill[prow * 2 + hh];
;     op[g] = dilo + (prow * 2 + hh) * 64 + d0;
;   }
;   float mx = fmaxf(ls[0], fmaxf(ls[1], ls[2]));
;   float e0 = fexp2(ls[0] - mx), e1 = fexp2(ls[1] - mx), e2 = fexp2(ls[2] - mx);
;   float inv = 1.f / (e0 + e1 + e2);
;   e0 *= inv; e1 *= inv; e2 *= inv;
;   bf16* cat = (bf16*)(p.ws + OFF_CAT) + ((size_t)(4 + hh) * NT + tokg) * 64 + d0;
;   f32x4 va[3][4];
; #pragma unroll
;   for (int g = 0; g < 3; ++g)
; #pragma unroll
;     for (int q = 0; q < 4; ++q) va[g][q] = *(const f32x4*)(op[g] + 4 * q);
;   __builtin_amdgcn_sched_barrier(0);
;   u32x4 o0, o1;
; #pragma unroll
;   for (int q = 0; q < 4; ++q) {
;     const f32x4 a = va[0][q], bb = va[1][q], cc = va[2][q];
;     float v0 = e0 * a[0] + e1 * bb[0] + e2 * cc[0], v1 = e0 * a[1] + e1 * bb[1] + e2 * cc[1];
;     float v2 = e0 * a[2] + e1 * bb[2] + e2 * cc[2], v3 = e0 * a[3] + e1 * bb[3] + e2 * cc[3];
;     if (q < 2) { o0[2 * q] = pack2(v0, v1); o0[2 * q + 1] = pack2(v2, v3); }
;     else { o1[2 * (q - 2)] = pack2(v0, v1); o1[2 * (q - 2) + 1] = pack2(v2, v3); }
;   }
;   *(u32x4*)cat = o0; *(u32x4*)(cat + 8) = o1;
; __global__ void __launch_bounds__(512, 2) fwd_megakernel(Params p) {
;     ...
;       for (;;) {
;         __syncthreads();
;         if (threadIdx.x == 0) *qslot = (int)atomicAdd(qcnt, 1u);
;         __syncthreads();
;         const int q = *qslot;
;         if (q >= qtotal) break;
.LBB0_392:
	s_or_b64 exec, exec, s[2:3]
	s_mov_b64 s[2:3], src_shared_base
	s_waitcnt vmcnt(0)
	v_readfirstlane_b32 s2, v2
	s_nop 1
	v_add_u32_e32 v0, s2, v0
	v_mov_b32_e32 v2, 0x21040
	ds_write_b32 v2, v0
	s_waitcnt lgkmcnt(0)
.LBB0_393:
	s_or_b64 exec, exec, s[0:1]
	s_add_i32 s0, 0, 0x21040
	v_readlane_b32 s2, v254, 40
	s_cmp_lg_u32 s0, -1
	v_readlane_b32 s3, v254, 41
	s_cselect_b32 s0, s0, 0
	s_cselect_b32 s1, s3, 0
	v_mov_b32_e32 v2, s0
	v_mov_b32_e32 v3, s1
	s_waitcnt lgkmcnt(0)
	s_barrier
	ds_read_b32 v0, v2
	v_readlane_b32 s0, v255, 36
	s_waitcnt lgkmcnt(0)
	s_nop 0
	v_cmp_gt_i32_e32 vcc, s0, v0
	s_mov_b64 s[0:1], -1
	s_mov_b64 s[2:3], exec
	v_writelane_b32 v255, s2, 44
	s_nop 1
	v_writelane_b32 v255, s3, 45
	s_and_b64 s[2:3], s[2:3], vcc
	s_mov_b64 exec, s[2:3]
	s_cbranch_execz .LBB0_388
	s_movk_i32 s0, 0x17f
	v_cmp_lt_i32_e32 vcc, s0, v0
	s_and_saveexec_b64 s[0:1], vcc
	s_xor_b64 s[6:7], exec, s[0:1]
	s_cbranch_execz .LBB0_449
	v_readlane_b32 s0, v255, 35
	s_nop 1
	v_cmp_le_i32_e32 vcc, s0, v0
	s_and_saveexec_b64 s[0:1], vcc
	s_xor_b64 s[0:1], exec, s[0:1]
	s_cbranch_execz .LBB0_397
	v_readlane_b32 s2, v255, 37
	v_mov_b32_e32 v2, v228
	s_mov_b64 s[4:5], 0x4000
	v_add_u32_e32 v0, s2, v0
	v_ashrrev_i32_e32 v12, 3, v2
	v_lshl_add_u32 v50, v0, 6, v12
	v_lshlrev_b32_e32 v0, 4, v2
	v_and_b32_e32 v53, 48, v0
	v_ashrrev_i32_e32 v0, 13, v50
	v_bfe_u32 v51, v2, 2, 1
	v_mul_i32_i24_e32 v2, 3, v0
	v_readlane_b32 s2, v254, 48
	v_and_b32_e32 v8, 0x1fff, v50
	v_lshlrev_b32_e32 v0, 2, v53
	v_readlane_b32 s3, v254, 49
	v_ashrrev_i32_e32 v3, 31, v2
	v_lshlrev_b64 v[6:7], 14, v[2:3]
	v_lshl_add_u64 v[4:5], s[2:3], 0, v[0:1]
	v_lshlrev_b32_e32 v0, 1, v8
	v_readlane_b32 s2, v254, 50
	v_or3_b32 v6, v6, v0, v51
	v_readlane_b32 s3, v254, 51
	v_lshlrev_b32_e32 v0, 11, v12
	v_and_b32_e32 v0, 0x1800, v0
	v_lshl_add_u64 v[8:9], v[6:7], 2, s[2:3]
	v_lshlrev_b64 v[6:7], 8, v[6:7]
	v_lshl_add_u64 v[14:15], v[4:5], 0, v[6:7]
	v_bfe_u32 v6, v50, 2, 11
	v_lshlrev_b64 v[2:3], 13, v[2:3]
	v_or3_b32 v6, v2, v6, v0
	v_mov_b32_e32 v7, v3
	v_lshlrev_b64 v[6:7], 1, v[6:7]
	v_or_b32_e32 v6, v6, v51
	v_lshl_add_u64 v[6:7], v[6:7], 0, s[4:5]
	v_lshl_add_u64 v[10:11], v[6:7], 2, s[2:3]
	v_lshlrev_b64 v[6:7], 8, v[6:7]
	v_lshlrev_b32_e32 v0, 9, v12
	v_lshl_add_u64 v[30:31], v[4:5], 0, v[6:7]
	v_and_b32_e32 v0, 0x1e00, v0
	v_bfe_u32 v6, v50, 4, 9
	v_or3_b32 v2, v2, v6, v0
	v_lshlrev_b64 v[2:3], 1, v[2:3]
	v_or_b32_e32 v2, v2, v51
	s_mov_b64 s[4:5], 0x8000
	v_lshl_add_u64 v[2:3], v[2:3], 0, s[4:5]
	v_lshl_add_u64 v[34:35], v[2:3], 2, s[2:3]
	v_lshlrev_b64 v[2:3], 8, v[2:3]
	v_lshl_add_u64 v[46:47], v[4:5], 0, v[2:3]
	global_load_dword v0, v[8:9], off
	global_load_dwordx4 v[2:5], v[14:15], off
	global_load_dword v52, v[10:11], off
	s_nop 0
	global_load_dwordx4 v[6:9], v[14:15], off offset:48
	global_load_dwordx4 v[10:13], v[14:15], off offset:16
	s_nop 0
	global_load_dwordx4 v[14:17], v[14:15], off offset:32
	s_nop 0
	global_load_dwordx4 v[18:21], v[30:31], off offset:16
	global_load_dwordx4 v[22:25], v[30:31], off
	global_load_dwordx4 v[26:29], v[30:31], off offset:48
	s_nop 0
	global_load_dwordx4 v[30:33], v[30:31], off offset:32
	s_nop 0
	global_load_dword v54, v[34:35], off
	s_nop 0
	global_load_dwordx4 v[34:37], v[46:47], off
	global_load_dwordx4 v[38:41], v[46:47], off offset:48
	global_load_dwordx4 v[42:45], v[46:47], off offset:16
	s_nop 0
	global_load_dwordx4 v[46:49], v[46:47], off offset:32
	s_waitcnt vmcnt(4)
	v_max3_f32 v55, v0, v52, v54
	v_sub_f32_e32 v0, v0, v55
	v_sub_f32_e32 v52, v52, v55
	v_exp_f32_e32 v0, v0
	v_sub_f32_e32 v54, v54, v55
	v_exp_f32_e32 v52, v52
	v_exp_f32_e32 v54, v54
	v_add_f32_e32 v55, v0, v52
	v_add_f32_e32 v55, v54, v55
	v_div_scale_f32 v56, s[2:3], v55, v55, 1.0
	v_rcp_f32_e32 v57, v56
	v_readlane_b32 s2, v254, 58
	v_readlane_b32 s3, v254, 59
	v_fma_f32 v58, -v56, v57, 1.0
	v_fmac_f32_e32 v57, v58, v57
	v_div_scale_f32 v58, vcc, 1.0, v55, 1.0
	v_mul_f32_e32 v59, v58, v57
	v_fma_f32 v60, -v56, v59, v58
	v_fmac_f32_e32 v59, v60, v57
	v_fma_f32 v56, -v56, v59, v58
	v_div_fmas_f32 v56, v56, v57, v59
	v_div_fixup_f32 v55, v56, v55, 1.0
	v_mul_f32_e32 v52, v52, v55
	v_mul_f32_e32 v0, v0, v55
	v_pk_mul_f32 v[30:31], v[52:53], v[30:31] op_sel_hi:[0,1]
	v_pk_fma_f32 v[14:15], v[14:15], v[0:1], v[30:31] op_sel_hi:[1,0,1]
	v_pk_mul_f32 v[30:31], v[52:53], v[32:33] op_sel_hi:[0,1]
	v_mul_f32_e32 v54, v54, v55
	v_pk_fma_f32 v[16:17], v[16:17], v[0:1], v[30:31] op_sel_hi:[1,0,1]
	s_waitcnt vmcnt(0)
	v_pk_fma_f32 v[14:15], v[54:55], v[46:47], v[14:15] op_sel_hi:[0,1,1]
	v_pk_fma_f32 v[16:17], v[54:55], v[48:49], v[16:17] op_sel_hi:[0,1,1]
	v_cvt_pk_bf16_f32 v14, v14, v15
	v_cvt_pk_bf16_f32 v15, v16, v17
	v_pk_mul_f32 v[16:17], v[52:53], v[26:27] op_sel_hi:[0,1]
	v_pk_fma_f32 v[6:7], v[6:7], v[0:1], v[16:17] op_sel_hi:[1,0,1]
	s_nop 0
	v_pk_fma_f32 v[6:7], v[54:55], v[38:39], v[6:7] op_sel_hi:[0,1,1]
	v_cvt_pk_bf16_f32 v16, v6, v7
	v_pk_mul_f32 v[6:7], v[52:53], v[28:29] op_sel_hi:[0,1]
	v_pk_fma_f32 v[6:7], v[8:9], v[0:1], v[6:7] op_sel_hi:[1,0,1]
	s_nop 0
	v_pk_fma_f32 v[6:7], v[54:55], v[40:41], v[6:7] op_sel_hi:[0,1,1]
	v_cvt_pk_bf16_f32 v17, v6, v7
	v_pk_mul_f32 v[6:7], v[22:23], v[52:53] op_sel_hi:[1,0]
	s_nop 0
	v_pk_fma_f32 v[2:3], v[2:3], v[0:1], v[6:7] op_sel_hi:[1,0,1]
	v_pk_mul_f32 v[6:7], v[24:25], v[52:53] op_sel_hi:[1,0]
	v_pk_fma_f32 v[2:3], v[54:55], v[34:35], v[2:3] op_sel_hi:[0,1,1]
	v_pk_fma_f32 v[4:5], v[4:5], v[0:1], v[6:7] op_sel_hi:[1,0,1]
	v_cvt_pk_bf16_f32 v2, v2, v3
	v_pk_fma_f32 v[4:5], v[54:55], v[36:37], v[4:5] op_sel_hi:[0,1,1]
	v_cvt_pk_bf16_f32 v3, v4, v5
	v_pk_mul_f32 v[4:5], v[18:19], v[52:53] op_sel_hi:[1,0]
	v_pk_mul_f32 v[6:7], v[20:21], v[52:53] op_sel_hi:[1,0]
	v_pk_fma_f32 v[4:5], v[10:11], v[0:1], v[4:5] op_sel_hi:[1,0,1]
	v_pk_fma_f32 v[6:7], v[12:13], v[0:1], v[6:7] op_sel_hi:[1,0,1]
	v_mov_b32_e32 v0, 0x10000
	v_pk_fma_f32 v[4:5], v[54:55], v[42:43], v[4:5] op_sel_hi:[0,1,1]
	v_pk_fma_f32 v[6:7], v[54:55], v[44:45], v[6:7] op_sel_hi:[0,1,1]
	v_lshl_or_b32 v0, v51, 14, v0
	v_ashrrev_i32_e32 v51, 31, v50
	v_cvt_pk_bf16_f32 v4, v4, v5
	v_cvt_pk_bf16_f32 v5, v6, v7
	v_lshl_add_u64 v[6:7], v[0:1], 0, v[50:51]
	v_lshlrev_b64 v[6:7], 7, v[6:7]
	v_lshl_add_u64 v[6:7], s[2:3], 0, v[6:7]
	v_lshlrev_b32_e32 v0, 1, v53
	v_lshl_add_u64 v[6:7], v[6:7], 0, v[0:1]
	global_store_dwordx4 v[6:7], v[2:5], off
	global_store_dwordx4 v[6:7], v[14:17], off offset:16
